# attention softmax denominator by f32 VALU adds of exp2 outputs instead of a ones-MFMA; plus SwiGLU epilogue load hoist
# speedup vs baseline: 1.0125x; 1.0027x over previous
.LBB0_106:
	s_lshl_b64 s[14:15], s[4:5], 17
	s_lshl_b32 s4, s37, 13
	v_lshl_add_u64 v[48:49], v[146:147], 0, s[14:15]
	s_add_i32 s4, s33, s4
	v_lshl_add_u64 v[48:49], v[48:49], 0, s[20:21]
	s_add_i32 m0, s4, 0x9000
	s_mul_i32 s4, s43, 0x3000
	global_load_lds_dwordx4 v[48:49], off
	s_add_i32 s4, s4, 16
	v_add_u32_e32 v52, s4, v149
	ds_read_b128 v[48:51], v52
	ds_read_b128 v[106:109], v52 offset:32
	ds_read_b128 v[64:67], v52 offset:6144
	ds_read_b128 v[110:113], v52 offset:6176
	ds_read_b128 v[114:117], v52 offset:64
	ds_read_b128 v[118:121], v52 offset:96
	ds_read_b128 v[122:125], v52 offset:6208
	ds_read_b128 v[126:129], v52 offset:6240
	v_add_u32_e32 v52, s4, v150
	ds_read_b128 v[132:135], v52
	ds_read_b128 v[160:163], v52 offset:6144
	v_add_u32_e32 v52, s4, v151
	ds_read_b128 v[164:167], v52
	ds_read_b128 v[168:171], v52 offset:6144
	s_setprio 1
	s_waitcnt lgkmcnt(0)
	v_mfma_f32_32x32x16_bf16 v[48:63], v[48:51], v[82:85], 0
	v_mfma_f32_32x32x16_bf16 v[64:79], v[64:67], v[82:85], 0
	v_mfma_f32_32x32x16_bf16 v[48:63], v[106:109], v[86:89], v[48:63]
	v_mfma_f32_32x32x16_bf16 v[64:79], v[110:113], v[86:89], v[64:79]
	v_mfma_f32_32x32x16_bf16 v[48:63], v[114:117], v[90:93], v[48:63]
	v_mfma_f32_32x32x16_bf16 v[64:79], v[122:125], v[90:93], v[64:79]
	v_mfma_f32_32x32x16_bf16 v[48:63], v[118:121], v[94:97], v[48:63]
	v_mfma_f32_32x32x16_bf16 v[64:79], v[126:129], v[94:97], v[64:79]
	v_mfma_f32_32x32x16_bf16 v[48:63], v[132:135], v[98:101], v[48:63]
	v_mfma_f32_32x32x16_bf16 v[64:79], v[160:163], v[98:101], v[64:79]
	v_mfma_f32_32x32x16_bf16 v[48:63], v[164:167], v[102:105], v[48:63]
	v_mfma_f32_32x32x16_bf16 v[64:79], v[168:171], v[102:105], v[64:79]
	s_setprio 0
	v_lshl_add_u32 v108, s43, 13, v131
	ds_read_b64_tr_b16 v[132:133], v108 offset:0
	ds_read_b64_tr_b16 v[134:135], v108 offset:1024
	ds_read_b64_tr_b16 v[160:161], v108 offset:64
	ds_read_b64_tr_b16 v[162:163], v108 offset:1088
	ds_read_b64_tr_b16 v[126:127], v108 offset:2048
	ds_read_b64_tr_b16 v[128:129], v108 offset:3072
	ds_read_b64_tr_b16 v[122:123], v108 offset:2112
	ds_read_b64_tr_b16 v[124:125], v108 offset:3136
	ds_read_b64_tr_b16 v[118:119], v108 offset:4096
	ds_read_b64_tr_b16 v[120:121], v108 offset:5120
	ds_read_b64_tr_b16 v[114:115], v108 offset:4160
	ds_read_b64_tr_b16 v[116:117], v108 offset:5184
	ds_read_b64_tr_b16 v[110:111], v108 offset:6144
	ds_read_b64_tr_b16 v[112:113], v108 offset:7168
	ds_read_b64_tr_b16 v[106:107], v108 offset:6208
	ds_read_b64_tr_b16 v[108:109], v108 offset:7232
	s_nop 8
	v_exp_f32_e32 v50, v50
	v_exp_f32_e32 v51, v51
	v_exp_f32_e32 v52, v52
	v_exp_f32_e32 v53, v53
	v_exp_f32_e32 v54, v54
	v_exp_f32_e32 v55, v55
	v_exp_f32_e32 v48, v48
	v_exp_f32_e32 v49, v49
	v_add_f32_e32 v32, v32, v50
	v_add_f32_e32 v33, v33, v51
	v_add_f32_e32 v34, v34, v52
	v_add_f32_e32 v35, v35, v53
	v_add_f32_e32 v32, v32, v54
	v_add_f32_e32 v33, v33, v55
	v_add_f32_e32 v34, v34, v48
	v_add_f32_e32 v35, v35, v49
	s_waitcnt lgkmcnt(0)
	v_cvt_pk_bf16_f32 v48, v48, v49
	v_cvt_pk_bf16_f32 v49, v50, v51
	v_cvt_pk_bf16_f32 v50, v52, v53
	v_cvt_pk_bf16_f32 v51, v54, v55
	s_nop 1
	v_mfma_f32_32x32x16_bf16 v[0:15], v[132:135], v[48:51], v[0:15]
	v_exp_f32_e32 v56, v56
	v_exp_f32_e32 v57, v57
	v_exp_f32_e32 v58, v58
	v_exp_f32_e32 v59, v59
	v_exp_f32_e32 v60, v60
	v_exp_f32_e32 v61, v61
	v_exp_f32_e32 v62, v62
	v_mfma_f32_32x32x16_bf16 v[16:31], v[160:163], v[48:51], v[16:31]
	v_exp_f32_e32 v63, v63
	v_exp_f32_e32 v64, v64
	v_exp_f32_e32 v65, v65
	v_exp_f32_e32 v66, v66
	v_exp_f32_e32 v67, v67
	v_exp_f32_e32 v68, v68
	v_exp_f32_e32 v69, v69
	v_add_f32_e32 v32, v32, v56
	v_add_f32_e32 v33, v33, v57
	v_add_f32_e32 v34, v34, v58
	v_add_f32_e32 v35, v35, v59
	v_add_f32_e32 v32, v32, v60
	v_add_f32_e32 v33, v33, v61
	v_add_f32_e32 v34, v34, v62
	v_add_f32_e32 v35, v35, v63
	v_cvt_pk_bf16_f32 v48, v56, v57
	v_cvt_pk_bf16_f32 v49, v58, v59
	v_cvt_pk_bf16_f32 v50, v60, v61
	v_cvt_pk_bf16_f32 v51, v62, v63
	v_exp_f32_e32 v70, v70
	v_exp_f32_e32 v71, v71
	v_exp_f32_e32 v72, v72
	v_mfma_f32_32x32x16_bf16 v[0:15], v[126:129], v[48:51], v[0:15]
	v_exp_f32_e32 v73, v73
	v_exp_f32_e32 v74, v74
	v_exp_f32_e32 v75, v75
	v_exp_f32_e32 v76, v76
	v_exp_f32_e32 v77, v77
	v_exp_f32_e32 v78, v78
	v_exp_f32_e32 v79, v79
	v_mfma_f32_32x32x16_bf16 v[16:31], v[122:125], v[48:51], v[16:31]
	s_mov_b64 s[14:15], -1
	s_and_b64 vcc, exec, s[40:41]
	v_add_f32_e32 v32, v32, v64
	v_add_f32_e32 v33, v33, v65
	v_add_f32_e32 v34, v34, v66
	v_add_f32_e32 v35, v35, v67
	v_add_f32_e32 v32, v32, v68
	v_add_f32_e32 v33, v33, v69
	v_add_f32_e32 v34, v34, v70
	v_add_f32_e32 v35, v35, v71
	v_cvt_pk_bf16_f32 v48, v64, v65
	v_cvt_pk_bf16_f32 v49, v66, v67
	v_cvt_pk_bf16_f32 v50, v68, v69
	v_cvt_pk_bf16_f32 v51, v70, v71
	s_nop 0
	v_mfma_f32_32x32x16_bf16 v[0:15], v[118:121], v[48:51], v[0:15]
	v_mfma_f32_32x32x16_bf16 v[16:31], v[114:117], v[48:51], v[16:31]
	v_add_f32_e32 v32, v32, v72
	v_add_f32_e32 v33, v33, v73
	v_add_f32_e32 v34, v34, v74
	v_add_f32_e32 v35, v35, v75
	v_add_f32_e32 v32, v32, v76
	v_add_f32_e32 v33, v33, v77
	v_add_f32_e32 v34, v34, v78
	v_add_f32_e32 v35, v35, v79
	v_cvt_pk_bf16_f32 v48, v72, v73
	v_cvt_pk_bf16_f32 v49, v74, v75
	v_cvt_pk_bf16_f32 v50, v76, v77
	v_cvt_pk_bf16_f32 v51, v78, v79
	s_nop 0
	v_mfma_f32_32x32x16_bf16 v[0:15], v[110:113], v[48:51], v[0:15]
	v_mfma_f32_32x32x16_bf16 v[16:31], v[106:109], v[48:51], v[16:31]
	s_cbranch_vccz .LBB0_108
	s_waitcnt vmcnt(2)
	s_mov_b64 s[14:15], 0

.LBB0_120:
	s_nop 6
	v_exp_f32_e32 v50, v50
	v_exp_f32_e32 v51, v51
	v_exp_f32_e32 v52, v52
	v_exp_f32_e32 v53, v53
	v_exp_f32_e32 v54, v54
	v_exp_f32_e32 v55, v55
	v_exp_f32_e32 v48, v48
	v_exp_f32_e32 v49, v49
	v_add_f32_e32 v32, v32, v50
	v_add_f32_e32 v33, v33, v51
	v_add_f32_e32 v34, v34, v52
	v_add_f32_e32 v35, v35, v53
	v_add_f32_e32 v32, v32, v54
	v_add_f32_e32 v33, v33, v55
	v_add_f32_e32 v34, v34, v48
	v_add_f32_e32 v35, v35, v49
	s_waitcnt lgkmcnt(0)
	v_cvt_pk_bf16_f32 v48, v48, v49
	v_cvt_pk_bf16_f32 v49, v50, v51
	v_cvt_pk_bf16_f32 v50, v52, v53
	v_cvt_pk_bf16_f32 v51, v54, v55
	s_nop 1
	v_mfma_f32_32x32x16_bf16 v[0:15], v[134:137], v[48:51], v[0:15]
	v_exp_f32_e32 v56, v56
	v_exp_f32_e32 v57, v57
	v_exp_f32_e32 v58, v58
	v_exp_f32_e32 v59, v59
	v_exp_f32_e32 v60, v60
	v_exp_f32_e32 v61, v61
	v_exp_f32_e32 v62, v62
	v_mfma_f32_32x32x16_bf16 v[16:31], v[130:133], v[48:51], v[16:31]
	v_exp_f32_e32 v63, v63
	v_exp_f32_e32 v64, v64
	v_exp_f32_e32 v65, v65
	v_exp_f32_e32 v66, v66
	v_exp_f32_e32 v67, v67
	v_exp_f32_e32 v68, v68
	v_exp_f32_e32 v69, v69
	v_add_f32_e32 v32, v32, v56
	v_add_f32_e32 v33, v33, v57
	v_add_f32_e32 v34, v34, v58
	v_add_f32_e32 v35, v35, v59
	v_add_f32_e32 v32, v32, v60
	v_add_f32_e32 v33, v33, v61
	v_add_f32_e32 v34, v34, v62
	v_add_f32_e32 v35, v35, v63
	v_cvt_pk_bf16_f32 v48, v56, v57
	v_cvt_pk_bf16_f32 v49, v58, v59
	v_cvt_pk_bf16_f32 v50, v60, v61
	v_cvt_pk_bf16_f32 v51, v62, v63
	v_exp_f32_e32 v70, v70
	v_exp_f32_e32 v71, v71
	v_exp_f32_e32 v72, v72
	v_mfma_f32_32x32x16_bf16 v[0:15], v[126:129], v[48:51], v[0:15]
	v_exp_f32_e32 v73, v73
	v_exp_f32_e32 v74, v74
	v_exp_f32_e32 v75, v75
	v_exp_f32_e32 v76, v76
	v_exp_f32_e32 v77, v77
	v_exp_f32_e32 v78, v78
	v_exp_f32_e32 v79, v79
	v_mfma_f32_32x32x16_bf16 v[16:31], v[122:125], v[48:51], v[16:31]
	v_add_f32_e32 v32, v32, v64
	v_add_f32_e32 v33, v33, v65
	v_add_f32_e32 v34, v34, v66
	v_add_f32_e32 v35, v35, v67
	v_add_f32_e32 v32, v32, v68
	v_add_f32_e32 v33, v33, v69
	v_add_f32_e32 v34, v34, v70
	v_add_f32_e32 v35, v35, v71
	v_cvt_pk_bf16_f32 v48, v64, v65
	v_cvt_pk_bf16_f32 v49, v66, v67
	v_cvt_pk_bf16_f32 v50, v68, v69
	v_cvt_pk_bf16_f32 v51, v70, v71
	s_nop 0
	v_mfma_f32_32x32x16_bf16 v[0:15], v[118:121], v[48:51], v[0:15]
	v_mfma_f32_32x32x16_bf16 v[16:31], v[114:117], v[48:51], v[16:31]
	v_add_f32_e32 v32, v32, v72
	v_add_f32_e32 v33, v33, v73
	v_add_f32_e32 v34, v34, v74
	v_add_f32_e32 v35, v35, v75
	v_add_f32_e32 v32, v32, v76
	v_add_f32_e32 v33, v33, v77
	v_add_f32_e32 v34, v34, v78
	v_add_f32_e32 v35, v35, v79
	v_cvt_pk_bf16_f32 v48, v72, v73
	v_cvt_pk_bf16_f32 v49, v74, v75
	v_cvt_pk_bf16_f32 v50, v76, v77
	v_cvt_pk_bf16_f32 v51, v78, v79
	s_nop 0
	v_mfma_f32_32x32x16_bf16 v[0:15], v[110:113], v[48:51], v[0:15]
	v_mfma_f32_32x32x16_bf16 v[16:31], v[106:109], v[48:51], v[16:31]
	s_mov_b64 s[14:15], -1
	s_and_b64 vcc, exec, s[40:41]
	s_cbranch_vccnz .LBB0_126

.LBB0_127:
	v_add_f32_e32 v32, v32, v33
	v_add_f32_e32 v34, v34, v35
	v_add_f32_e32 v32, v32, v34
	ds_bpermute_b32 v33, v143, v32
	s_waitcnt lgkmcnt(0)
	v_add_f32_e32 v32, v32, v33
	s_nop 2
	v_div_scale_f32 v33, s[6:7], v32, v32, 1.0
	v_rcp_f32_e32 v34, v33
	s_lshl_b32 s4, s30, 7
	v_lshlrev_b32_e32 v80, 1, v148
	s_waitcnt vmcnt(0)
	v_fma_f32 v35, -v33, v34, 1.0
	v_fmac_f32_e32 v34, v35, v34
	v_div_scale_f32 v35, vcc, 1.0, v32, 1.0
	v_mul_f32_e32 v36, v35, v34
	v_fma_f32 v37, -v33, v36, v35
	v_fmac_f32_e32 v36, v37, v34
	v_fma_f32 v33, -v33, v36, v35
	v_div_fmas_f32 v33, v33, v34, v36
	v_div_fixup_f32 v34, v33, v32, 1.0
	v_lshlrev_b64 v[32:33], 11, v[140:141]
	v_mul_f32_e32 v0, v34, v0
	v_mul_f32_e32 v1, v34, v1
	v_lshl_add_u64 v[32:33], s[88:89], 0, v[32:33]
	v_mul_f32_e32 v16, v34, v16
	v_mul_f32_e32 v35, v0, v0
	v_mul_f32_e32 v17, v34, v17
	v_mul_f32_e32 v36, v1, v1
	v_lshl_add_u64 v[32:33], v[32:33], 0, s[4:5]
	v_fmac_f32_e32 v35, v16, v16
	v_fmac_f32_e32 v36, v17, v17
	v_mul_f32_e32 v2, v34, v2
	s_barrier
	v_lshl_add_u64 v[32:33], v[32:33], 0, v[80:81]
	v_add_f32_e32 v35, v35, v36
	v_mul_f32_e32 v18, v34, v18
	v_mul_f32_e32 v36, v2, v2
	v_cvt_pk_bf16_f32 v0, v0, v1
	v_fmac_f32_e32 v36, v18, v18
	v_mul_f32_e32 v3, v34, v3
	v_cvt_pk_bf16_f32 v1, v2, v3
	global_store_dwordx2 v[32:33], v[0:1], off offset:1024
	v_cvt_pk_bf16_f32 v0, v16, v17
	v_add_f32_e32 v35, v36, v35
	v_mul_f32_e32 v19, v34, v19
	v_mul_f32_e32 v36, v3, v3
	v_cvt_pk_bf16_f32 v1, v18, v19
	global_store_dwordx2 v[32:33], v[0:1], off offset:1088
	v_mul_f32_e32 v0, v34, v4
	v_fmac_f32_e32 v36, v19, v19
	v_mul_f32_e32 v2, v34, v20
	v_mul_f32_e32 v1, v0, v0
	v_mul_f32_e32 v3, v34, v5
	v_add_f32_e32 v35, v36, v35
	v_fmac_f32_e32 v1, v2, v2
	v_mul_f32_e32 v4, v34, v21
	v_mul_f32_e32 v5, v3, v3
	v_add_f32_e32 v1, v1, v35
	v_fmac_f32_e32 v5, v4, v4
	v_add_f32_e32 v1, v5, v1
	v_mul_f32_e32 v5, v34, v6
	v_mul_f32_e32 v6, v34, v22
	v_mul_f32_e32 v16, v5, v5
	v_fmac_f32_e32 v16, v6, v6
	v_mul_f32_e32 v7, v34, v7
	v_add_f32_e32 v1, v16, v1
	v_mul_f32_e32 v16, v34, v23
	v_mul_f32_e32 v17, v7, v7
	v_fmac_f32_e32 v17, v16, v16
	v_cvt_pk_bf16_f32 v0, v0, v3
	v_add_f32_e32 v17, v17, v1
	v_cvt_pk_bf16_f32 v1, v5, v7
	global_store_dwordx2 v[32:33], v[0:1], off offset:1040
	v_cvt_pk_bf16_f32 v0, v2, v4
	v_cvt_pk_bf16_f32 v1, v6, v16
	global_store_dwordx2 v[32:33], v[0:1], off offset:1104
	v_mul_f32_e32 v0, v34, v8
	v_mul_f32_e32 v2, v34, v24
	v_mul_f32_e32 v1, v0, v0
	v_mul_f32_e32 v3, v34, v9
	v_fmac_f32_e32 v1, v2, v2
	v_mul_f32_e32 v4, v34, v25
	v_mul_f32_e32 v5, v3, v3
	v_add_f32_e32 v1, v1, v17
	v_fmac_f32_e32 v5, v4, v4
	v_add_f32_e32 v1, v5, v1
	v_mul_f32_e32 v5, v34, v10
	v_mul_f32_e32 v6, v34, v26
	v_mul_f32_e32 v7, v5, v5
	v_fmac_f32_e32 v7, v6, v6
	v_add_f32_e32 v1, v7, v1
	v_mul_f32_e32 v7, v34, v11
	v_mul_f32_e32 v8, v34, v27
	v_mul_f32_e32 v9, v7, v7
	v_fmac_f32_e32 v9, v8, v8
	v_add_f32_e32 v9, v9, v1
	v_cvt_pk_bf16_f32 v0, v0, v3
	v_cvt_pk_bf16_f32 v1, v5, v7
	global_store_dwordx2 v[32:33], v[0:1], off offset:1056
	v_cvt_pk_bf16_f32 v0, v2, v4
	v_cvt_pk_bf16_f32 v1, v6, v8
	global_store_dwordx2 v[32:33], v[0:1], off offset:1120
	v_mul_f32_e32 v1, v34, v12
	v_mul_f32_e32 v4, v34, v28
	v_mul_f32_e32 v0, v1, v1
	v_mul_f32_e32 v2, v34, v13
	v_fmac_f32_e32 v0, v4, v4
	v_mul_f32_e32 v5, v34, v29
	v_mul_f32_e32 v3, v2, v2
	v_add_f32_e32 v0, v0, v9
	v_fmac_f32_e32 v3, v5, v5
	v_add_f32_e32 v0, v3, v0
	v_mul_f32_e32 v3, v34, v14
	v_mul_f32_e32 v6, v34, v30
	v_mul_f32_e32 v7, v3, v3
	v_fmac_f32_e32 v7, v6, v6
	v_add_f32_e32 v0, v7, v0
	v_mul_f32_e32 v7, v34, v15
	v_mul_f32_e32 v8, v34, v31
	v_mul_f32_e32 v9, v7, v7
	v_fmac_f32_e32 v9, v8, v8
	v_add_f32_e32 v0, v9, v0
	v_cvt_pk_bf16_f32 v2, v1, v2
	ds_bpermute_b32 v1, v143, v0
	v_cvt_pk_bf16_f32 v3, v3, v7
	v_cmp_gt_u32_e32 vcc, 32, v139
	global_store_dwordx2 v[32:33], v[2:3], off offset:1072
	v_cvt_pk_bf16_f32 v2, v4, v5
	v_cvt_pk_bf16_f32 v3, v6, v8
	global_store_dwordx2 v[32:33], v[2:3], off offset:1136
	s_and_saveexec_b64 s[6:7], vcc
	s_cbranch_execz .LBB0_97
	v_readlane_b32 s10, v252, 28
	v_readlane_b32 s11, v252, 29
	s_waitcnt lgkmcnt(0)
	v_add_f32_e32 v2, v0, v1
	v_lshl_add_u64 v[0:1], v[140:141], 2, s[10:11]
	global_atomic_add_f32 v[0:1], v2, off
	s_branch .LBB0_97
